# three P1 conversion classes, fractions 1/8 first, 2/8 between the GEMM1 calls, 5/8 after
# speedup vs baseline: 1.0127x; 1.0068x over previous
_Z3fwd4Args:
	v_writelane_b32 v249, s0, 0
	v_writelane_b32 v249, s1, 1
	v_writelane_b32 v249, s2, 2
	v_mov_b32_e32 v250, v0
	s_and_b32 s98, s2, 7
	s_movk_i32 s101, 0x100
	s_cmp_lt_u32 s98, 3
	s_cselect_b32 s101, 0x400, s101
	s_cmp_lt_u32 s98, 1
	s_cselect_b32 s101, 0, s101
